# attention: head V-fragment reads issued a step early together with bias init ahead of the mid-step barrier
# baseline (speedup 1.0000x reference)
.Lat_nre:
	v_xor_b32_e32 v186, 0x80, v186
	v_xor_b32_e32 v187, 0x80, v187
	v_xor_b32_e32 v188, 0x80, v188
	v_xor_b32_e32 v189, 0x80, v189
	v_cvt_f32_u32_e32 v204, s13
	v_mov_b32_e32 v165, v164
	v_fma_f32 v204, v172, v204, v179
	v_add_f32_e32 v208, v173, v204
	v_add_f32_e32 v212, v173, v208
	v_add_f32_e32 v216, v173, v212
	v_add_f32_e32 v205, v172, v204
	v_add_f32_e32 v209, v172, v208
	v_add_f32_e32 v213, v172, v212
	v_add_f32_e32 v217, v172, v216
	v_pk_add_f32 v[206:207], v[162:163], v[204:205] op_sel_hi:[1,0]
	v_pk_add_f32 v[210:211], v[162:163], v[208:209] op_sel_hi:[1,0]
	v_pk_add_f32 v[214:215], v[162:163], v[212:213] op_sel_hi:[1,0]
	v_pk_add_f32 v[218:219], v[162:163], v[216:217] op_sel_hi:[1,0]
	v_pk_add_f32 v[222:223], v[164:165], v[206:207]
	v_pk_add_f32 v[220:221], v[166:167], v[204:205]
	v_pk_add_f32 v[226:227], v[164:165], v[210:211]
	v_pk_add_f32 v[224:225], v[164:165], v[208:209]
	v_pk_add_f32 v[230:231], v[164:165], v[214:215]
	v_pk_add_f32 v[228:229], v[164:165], v[212:213]
	v_pk_add_f32 v[234:235], v[164:165], v[218:219]
	v_pk_add_f32 v[232:233], v[164:165], v[216:217]
	s_addk_i32 s13, 0x40
	s_waitcnt lgkmcnt(0)
	s_barrier
	ds_read_b128 v[236:239], v186 offset:49152
	ds_read_b128 v[240:243], v186 offset:57344
	v_exp_f32_e32 v80, v80
	s_waitcnt lgkmcnt(1)
	v_mfma_f32_32x32x16_bf16 v[204:219], v[236:239], v[104:107], v[204:219]
	ds_read_b128 v[236:239], v187 offset:49152
	v_exp_f32_e32 v81, v81
	v_pk_add_f32 v[170:171], v[170:171], v[78:79]
	v_exp_f32_e32 v82, v82
	s_waitcnt lgkmcnt(1)
	v_mfma_f32_32x32x16_bf16 v[220:235], v[240:243], v[104:107], v[220:235]
	ds_read_b128 v[240:243], v187 offset:57344
	v_exp_f32_e32 v83, v83
	v_pk_add_f32 v[170:171], v[170:171], v[80:81]
	v_exp_f32_e32 v84, v84
	v_exp_f32_e32 v85, v85
	s_waitcnt lgkmcnt(1)
	v_mfma_f32_32x32x16_bf16 v[204:219], v[236:239], v[108:111], v[204:219]
	ds_read_b128 v[236:239], v188 offset:49152
	v_pk_add_f32 v[170:171], v[170:171], v[82:83]
	v_exp_f32_e32 v86, v86
	v_exp_f32_e32 v87, v87
	s_waitcnt lgkmcnt(1)
	v_mfma_f32_32x32x16_bf16 v[220:235], v[240:243], v[108:111], v[220:235]
	ds_read_b128 v[240:243], v188 offset:57344
	v_pk_add_f32 v[170:171], v[170:171], v[84:85]
	v_exp_f32_e32 v88, v88
	v_exp_f32_e32 v89, v89
	v_pk_add_f32 v[170:171], v[170:171], v[86:87]
	s_waitcnt lgkmcnt(1)
	v_mfma_f32_32x32x16_bf16 v[204:219], v[236:239], v[112:115], v[204:219]
	ds_read_b128 v[236:239], v189 offset:49152
	v_exp_f32_e32 v90, v90
	v_exp_f32_e32 v91, v91
	v_pk_add_f32 v[170:171], v[170:171], v[88:89]
	v_exp_f32_e32 v92, v92
	s_waitcnt lgkmcnt(1)
	v_mfma_f32_32x32x16_bf16 v[220:235], v[240:243], v[112:115], v[220:235]
	ds_read_b128 v[240:243], v189 offset:57344
	v_exp_f32_e32 v93, v93
	v_pk_add_f32 v[170:171], v[170:171], v[90:91]
	v_exp_f32_e32 v94, v94
	s_waitcnt lgkmcnt(1)
	v_mfma_f32_32x32x16_bf16 v[204:219], v[236:239], v[116:119], v[204:219]
	v_xor_b32_e32 v186, 0x80, v186
	v_xor_b32_e32 v187, 0x80, v187
	v_xor_b32_e32 v188, 0x80, v188
	v_xor_b32_e32 v189, 0x80, v189
	ds_read_b128 v[236:239], v186 offset:49152
	v_exp_f32_e32 v95, v95
	v_pk_add_f32 v[170:171], v[170:171], v[92:93]
	s_nop 0
	v_pk_add_f32 v[170:171], v[170:171], v[94:95]
	s_waitcnt lgkmcnt(1)
	v_mfma_f32_32x32x16_bf16 v[220:235], v[240:243], v[116:119], v[220:235]
	ds_read_b128 v[240:243], v186 offset:57344
	v_add_f32_e32 v249, v170, v171
	v_mov_b32_e32 v170, v249
	s_nop 1
	s_waitcnt lgkmcnt(1)
	v_mfma_f32_32x32x16_bf16 v[204:219], v[236:239], v[120:123], v[204:219]
	ds_read_b128 v[236:239], v187 offset:49152
	v_permlane32_swap_b32_e32 v249, v170
	v_cvt_pk_bf16_f32 v64, v64, v65
	v_cvt_pk_bf16_f32 v65, v66, v67
	v_cvt_pk_bf16_f32 v66, v68, v69
	s_waitcnt lgkmcnt(1)
	v_mfma_f32_32x32x16_bf16 v[220:235], v[240:243], v[120:123], v[220:235]
	ds_read_b128 v[240:243], v187 offset:57344
	v_cvt_pk_bf16_f32 v67, v70, v71
	v_cvt_pk_bf16_f32 v68, v72, v73
	v_cvt_pk_bf16_f32 v69, v74, v75
	s_waitcnt lgkmcnt(1)
	v_mfma_f32_32x32x16_bf16 v[204:219], v[236:239], v[124:127], v[204:219]
	ds_read_b128 v[236:239], v188 offset:49152
	v_cvt_pk_bf16_f32 v70, v76, v77
	v_cvt_pk_bf16_f32 v71, v78, v79
	v_cvt_pk_bf16_f32 v72, v80, v81
	v_cvt_pk_bf16_f32 v73, v82, v83
	s_waitcnt lgkmcnt(1)
	v_mfma_f32_32x32x16_bf16 v[220:235], v[240:243], v[124:127], v[220:235]
	ds_read_b128 v[240:243], v188 offset:57344
	v_cvt_pk_bf16_f32 v74, v84, v85
	v_cvt_pk_bf16_f32 v75, v86, v87
	v_cvt_pk_bf16_f32 v76, v88, v89
	s_waitcnt lgkmcnt(1)
	v_mfma_f32_32x32x16_bf16 v[204:219], v[236:239], v[128:131], v[204:219]
	ds_read_b128 v[236:239], v189 offset:49152
	v_cvt_pk_bf16_f32 v77, v90, v91
	v_cvt_pk_bf16_f32 v78, v92, v93
	v_cvt_pk_bf16_f32 v79, v94, v95
	v_add_u32_e32 v165, s7, v178
	ds_read_b64_tr_b16 v[80:81], v165 offset:0
	ds_read_b64_tr_b16 v[82:83], v165 offset:2048
	ds_read_b64_tr_b16 v[84:85], v165 offset:4096
	ds_read_b64_tr_b16 v[86:87], v165 offset:6144
	ds_read_b64_tr_b16 v[88:89], v165 offset:8192
	ds_read_b64_tr_b16 v[90:91], v165 offset:10240
	ds_read_b64_tr_b16 v[92:93], v165 offset:12288
	ds_read_b64_tr_b16 v[94:95], v165 offset:14336
	v_permlane32_swap_b32_e32 v64, v66
	s_waitcnt lgkmcnt(1)
	v_mfma_f32_32x32x16_bf16 v[220:235], v[240:243], v[128:131], v[220:235]
	ds_read_b128 v[240:243], v189 offset:57344
	v_permlane32_swap_b32_e32 v65, v67
	v_permlane32_swap_b32_e32 v68, v70
	v_permlane32_swap_b32_e32 v69, v71
	v_permlane32_swap_b32_e32 v72, v74
	s_waitcnt lgkmcnt(1)
	v_mfma_f32_32x32x16_bf16 v[204:219], v[236:239], v[132:135], v[204:219]
	v_permlane32_swap_b32_e32 v73, v75
	v_permlane32_swap_b32_e32 v76, v78
	v_permlane32_swap_b32_e32 v77, v79
	s_waitcnt lgkmcnt(0)
	v_mfma_f32_32x32x16_bf16 v[220:235], v[240:243], v[132:135], v[220:235]
	v_add_f32_e32 v171, v249, v170
	v_fmac_f32_e32 v171, v185, v202
	v_mov_b32_e32 v185, v171
	s_waitcnt vmcnt(0)
	v_add_u32_e32 v200, s8, v180
	v_add_u32_e32 v201, s8, v181
	ds_write_b128 v200, v[96:99]
	ds_write_b128 v201, v[100:103]
	s_and_b64 vcc, exec, s[34:35]
	s_cbranch_vccz .Lat_nwe
	ds_write_b128 v182, v[136:139] offset:32768
	ds_write_b128 v182, v[140:143] offset:40960

.Lat_nro:
	v_xor_b32_e32 v186, 0x80, v186
	v_xor_b32_e32 v187, 0x80, v187
	v_xor_b32_e32 v188, 0x80, v188
	v_xor_b32_e32 v189, 0x80, v189
	v_cvt_f32_u32_e32 v64, s13
	v_mov_b32_e32 v165, v164
	v_fma_f32 v64, v172, v64, v179
	v_add_f32_e32 v68, v173, v64
	v_add_f32_e32 v72, v173, v68
	v_add_f32_e32 v76, v173, v72
	v_add_f32_e32 v65, v172, v64
	v_add_f32_e32 v69, v172, v68
	v_add_f32_e32 v73, v172, v72
	v_add_f32_e32 v77, v172, v76
	v_pk_add_f32 v[66:67], v[162:163], v[64:65] op_sel_hi:[1,0]
	v_pk_add_f32 v[70:71], v[162:163], v[68:69] op_sel_hi:[1,0]
	v_pk_add_f32 v[74:75], v[162:163], v[72:73] op_sel_hi:[1,0]
	v_pk_add_f32 v[78:79], v[162:163], v[76:77] op_sel_hi:[1,0]
	v_pk_add_f32 v[82:83], v[164:165], v[66:67]
	v_pk_add_f32 v[80:81], v[166:167], v[64:65]
	v_pk_add_f32 v[86:87], v[164:165], v[70:71]
	v_pk_add_f32 v[84:85], v[164:165], v[68:69]
	v_pk_add_f32 v[90:91], v[164:165], v[74:75]
	v_pk_add_f32 v[88:89], v[164:165], v[72:73]
	v_pk_add_f32 v[94:95], v[164:165], v[78:79]
	v_pk_add_f32 v[92:93], v[164:165], v[76:77]
	s_addk_i32 s13, 0x40
	s_waitcnt lgkmcnt(0)
	s_barrier
	ds_read_b128 v[236:239], v186 offset:32768
	ds_read_b128 v[240:243], v186 offset:40960
	v_exp_f32_e32 v220, v220
	s_waitcnt lgkmcnt(1)
	v_mfma_f32_32x32x16_bf16 v[64:79], v[236:239], v[104:107], v[64:79]
	ds_read_b128 v[236:239], v187 offset:32768
	v_exp_f32_e32 v221, v221
	v_pk_add_f32 v[170:171], v[170:171], v[218:219]
	v_exp_f32_e32 v222, v222
	s_waitcnt lgkmcnt(1)
	v_mfma_f32_32x32x16_bf16 v[80:95], v[240:243], v[104:107], v[80:95]
	ds_read_b128 v[240:243], v187 offset:40960
	v_exp_f32_e32 v223, v223
	v_pk_add_f32 v[170:171], v[170:171], v[220:221]
	v_exp_f32_e32 v224, v224
	v_exp_f32_e32 v225, v225
	s_waitcnt lgkmcnt(1)
	v_mfma_f32_32x32x16_bf16 v[64:79], v[236:239], v[108:111], v[64:79]
	ds_read_b128 v[236:239], v188 offset:32768
	v_pk_add_f32 v[170:171], v[170:171], v[222:223]
	v_exp_f32_e32 v226, v226
	v_exp_f32_e32 v227, v227
	s_waitcnt lgkmcnt(1)
	v_mfma_f32_32x32x16_bf16 v[80:95], v[240:243], v[108:111], v[80:95]
	ds_read_b128 v[240:243], v188 offset:40960
	v_pk_add_f32 v[170:171], v[170:171], v[224:225]
	v_exp_f32_e32 v228, v228
	v_exp_f32_e32 v229, v229
	v_pk_add_f32 v[170:171], v[170:171], v[226:227]
	s_waitcnt lgkmcnt(1)
	v_mfma_f32_32x32x16_bf16 v[64:79], v[236:239], v[112:115], v[64:79]
	ds_read_b128 v[236:239], v189 offset:32768
	v_exp_f32_e32 v230, v230
	v_exp_f32_e32 v231, v231
	v_pk_add_f32 v[170:171], v[170:171], v[228:229]
	v_exp_f32_e32 v232, v232
	s_waitcnt lgkmcnt(1)
	v_mfma_f32_32x32x16_bf16 v[80:95], v[240:243], v[112:115], v[80:95]
	ds_read_b128 v[240:243], v189 offset:40960
	v_exp_f32_e32 v233, v233
	v_pk_add_f32 v[170:171], v[170:171], v[230:231]
	v_exp_f32_e32 v234, v234
	s_waitcnt lgkmcnt(1)
	v_mfma_f32_32x32x16_bf16 v[64:79], v[236:239], v[116:119], v[64:79]
	v_xor_b32_e32 v186, 0x80, v186
	v_xor_b32_e32 v187, 0x80, v187
	v_xor_b32_e32 v188, 0x80, v188
	v_xor_b32_e32 v189, 0x80, v189
	ds_read_b128 v[236:239], v186 offset:32768
	v_exp_f32_e32 v235, v235
	v_pk_add_f32 v[170:171], v[170:171], v[232:233]
	s_nop 0
	v_pk_add_f32 v[170:171], v[170:171], v[234:235]
	s_waitcnt lgkmcnt(1)
	v_mfma_f32_32x32x16_bf16 v[80:95], v[240:243], v[116:119], v[80:95]
	ds_read_b128 v[240:243], v186 offset:40960
	v_add_f32_e32 v249, v170, v171
	v_mov_b32_e32 v170, v249
	s_nop 1
	s_waitcnt lgkmcnt(1)
	v_mfma_f32_32x32x16_bf16 v[64:79], v[236:239], v[120:123], v[64:79]
	ds_read_b128 v[236:239], v187 offset:32768
	v_permlane32_swap_b32_e32 v249, v170
	v_cvt_pk_bf16_f32 v204, v204, v205
	v_cvt_pk_bf16_f32 v205, v206, v207
	v_cvt_pk_bf16_f32 v206, v208, v209
	s_waitcnt lgkmcnt(1)
	v_mfma_f32_32x32x16_bf16 v[80:95], v[240:243], v[120:123], v[80:95]
	ds_read_b128 v[240:243], v187 offset:40960
	v_cvt_pk_bf16_f32 v207, v210, v211
	v_cvt_pk_bf16_f32 v208, v212, v213
	v_cvt_pk_bf16_f32 v209, v214, v215
	s_waitcnt lgkmcnt(1)
	v_mfma_f32_32x32x16_bf16 v[64:79], v[236:239], v[124:127], v[64:79]
	ds_read_b128 v[236:239], v188 offset:32768
	v_cvt_pk_bf16_f32 v210, v216, v217
	v_cvt_pk_bf16_f32 v211, v218, v219
	v_cvt_pk_bf16_f32 v212, v220, v221
	v_cvt_pk_bf16_f32 v213, v222, v223
	s_waitcnt lgkmcnt(1)
	v_mfma_f32_32x32x16_bf16 v[80:95], v[240:243], v[124:127], v[80:95]
	ds_read_b128 v[240:243], v188 offset:40960
	v_cvt_pk_bf16_f32 v214, v224, v225
	v_cvt_pk_bf16_f32 v215, v226, v227
	v_cvt_pk_bf16_f32 v216, v228, v229
	s_waitcnt lgkmcnt(1)
	v_mfma_f32_32x32x16_bf16 v[64:79], v[236:239], v[128:131], v[64:79]
	ds_read_b128 v[236:239], v189 offset:32768
	v_cvt_pk_bf16_f32 v217, v230, v231
	v_cvt_pk_bf16_f32 v218, v232, v233
	v_cvt_pk_bf16_f32 v219, v234, v235
	v_add_u32_e32 v165, s7, v178
	ds_read_b64_tr_b16 v[220:221], v165 offset:0
	ds_read_b64_tr_b16 v[222:223], v165 offset:2048
	ds_read_b64_tr_b16 v[224:225], v165 offset:4096
	ds_read_b64_tr_b16 v[226:227], v165 offset:6144
	ds_read_b64_tr_b16 v[228:229], v165 offset:8192
	ds_read_b64_tr_b16 v[230:231], v165 offset:10240
	ds_read_b64_tr_b16 v[232:233], v165 offset:12288
	ds_read_b64_tr_b16 v[234:235], v165 offset:14336
	v_permlane32_swap_b32_e32 v204, v206
	s_waitcnt lgkmcnt(1)
	v_mfma_f32_32x32x16_bf16 v[80:95], v[240:243], v[128:131], v[80:95]
	ds_read_b128 v[240:243], v189 offset:40960
	v_permlane32_swap_b32_e32 v205, v207
	v_permlane32_swap_b32_e32 v208, v210
	v_permlane32_swap_b32_e32 v209, v211
	v_permlane32_swap_b32_e32 v212, v214
	s_waitcnt lgkmcnt(1)
	v_mfma_f32_32x32x16_bf16 v[64:79], v[236:239], v[132:135], v[64:79]
	v_permlane32_swap_b32_e32 v213, v215
	v_permlane32_swap_b32_e32 v216, v218
	v_permlane32_swap_b32_e32 v217, v219
	s_waitcnt lgkmcnt(0)
	v_mfma_f32_32x32x16_bf16 v[80:95], v[240:243], v[132:135], v[80:95]
	v_add_f32_e32 v171, v249, v170
	v_fmac_f32_e32 v171, v185, v202
	v_mov_b32_e32 v185, v171
	s_waitcnt vmcnt(0)
	s_and_b64 vcc, exec, s[34:35]
	s_cbranch_vccz .Lat_nwo
	v_add_u32_e32 v200, s8, v180
	v_add_u32_e32 v201, s8, v181
	ds_write_b128 v200, v[96:99]
	ds_write_b128 v201, v[100:103]
	ds_write_b128 v182, v[136:139] offset:49152
	ds_write_b128 v182, v[140:143] offset:57344
